# gainfix+P6/P14 prefetch+kv/gates epilogue hoists + w_br_ret moved to P1 idle round + 5632 w_ffn_in items moved from P0 to P11 idle half
# speedup vs baseline: 1.0002x; 1.0002x over previous
; __device__ __forceinline__ int wfi_src(int nb) { const int pn = nb >> 3, q = nb & 7; return (q >> 2) * DFF + pn * 128 + (q & 3) * 32; }
; __device__ __forceinline__ int win_src(int nb) { const int n0 = nb * 32; if (n0 < 1536) return n0; if (n0 < 1792) return n0 == 1536 ? 1536 : (n0 == 1664 ? 1568 : -1); return n0 - 192; }
; __global__ void __launch_bounds__(NWAVES * 64, 2) mk_fwd(Args args) {
;     ...
;         for (int it = gw; it < NITEMS; it += NGW) {
;             int r = it;
;             if (r < I_IN) { const int nblk = INP / 32, kb = r / nblk, nb = r % nblk; p0_item(in_w_in, INW, D, Win_t, win_src(nb), nb * 32, kb * 64, nullptr, scr, lane); continue; } r -= I_IN;
;             if (r < I_UQ) { const int nblk = 3072 / 32, kb = r / nblk, nb = r % nblk; p0_item(in_w_uq, 3072, 1024, Wuq_t, wuq_src(nb), nb * 32, kb * 64, in_q_norm_g, scr, lane); continue; } r -= I_UQ;
;             if (r < I_UKV) { const int nblk = 4096 / 32, kb = r / nblk, nb = r % nblk; p0_item(in_w_ukv, 4096, 512, Wukv_t, nb * 32, nb * 32, kb * 64, in_kv_norm_g, scr, lane); continue; } r -= I_UKV;
;             if (r < I_BM) { const int nblk = 4096 / 32, kb = r / nblk, nb = r % nblk; p0_item(in_w_br_mla, 4096, 2048, Wbm_t, nb * 32, nb * 32, kb * 64, nullptr, scr, lane); continue; } r -= I_BM;
;             if (r < 5 * I_SQ) { const int wsel = r / I_SQ; r -= wsel * I_SQ; const int nblk = 4096 / 32, kb = r / nblk, nb = r % nblk;
;                 const float* W = wsel == 0 ? in_w_br_ret : wsel == 1 ? in_w_o : wsel == 2 ? in_w_cq : wsel == 3 ? in_w_ck : in_w_cv;
;                 bf16_t* WT = wsel == 0 ? Wbr_t : wsel == 1 ? Wo_t : wsel == 2 ? Wcq_r : wsel == 3 ? Wck_t : Wcv_t;
;                 if (wsel == 2) p0_item_lnr(W, 4096, WT, nb * 32, kb * 64, in_ln1_g, in_ln1_b, S1V, C1V, lane);
;                 else p0_item(W, 4096, 4096, WT, nb * 32, nb * 32, kb * 64, nullptr, scr, lane);
;                 continue; } r -= 5 * I_SQ;
;             { const int nblk = DFF2 / 32, kb = r / nblk, nb = r % nblk; p0_item_ln(in_w_ffn_in, DFF2, D, Wfi_t, wfi_src(nb), nb * 32, kb * 64, in_ln2_g, in_ln2_b, S2V, C2V, scr, lane); }
;         }
.LBB0_13:
	s_add_i32 s25, s25, s72
	s_add_i32 s20, s20, s72
	s_add_i32 s18, s18, s21
	s_add_i32 s22, s22, s72
	s_add_i32 s64, s64, s72
	s_cmpk_lg_i32 s85, 0x100
	s_cbranch_scc1 .Lp0_noskip
	s_cmp_lt_i32 s25, 0xc800
	s_cbranch_scc1 .Lp0_noskip
	s_cmp_lt_i32 s25, 0xe800
	s_cbranch_scc1 .LBB0_13
.Lp0_noskip:
	s_cmpk_lg_i32 s85, 0x100
	s_cbranch_scc1 .Lp0_full
	s_cmp_gt_i32 s25, 0x1a7ff
	s_cbranch_scc1 .LBB0_117
.Lp0_full:
	s_cmp_gt_i32 s25, 0x1bdff
	s_cbranch_scc1 .LBB0_117

; #define CONV_WCO(lo_, hi_, w_, nw_) do { LAS float* scr_ = (LAS float*)(lds + wave * 16384); for (int r = (lo_) + (w_); r < (hi_); r += (nw_)) { const int nblk = 4096 / 32, kb = r / nblk, nb = r % nblk; \
;         p0_item(in_w_co, 4096, 4096, Wco_t, nb * 32, nb * 32, kb * 64, nullptr, scr_, lane); } } while (0)
; __global__ void __launch_bounds__(NWAVES * 64, 2) mk_fwd(Args args) {
;     ...
;         if (split && bx >= 224) CONV_WCO(0, I_SQ / 2, (bx - 224) * NWAVES + wave, 32 * NWAVES);
.LBB0_269:
	s_lshl_b32 s0, s84, 3
	s_add_i32 s4, s93, s0
	s_cmpk_gt_i32 s84, 0xdf
	v_readlane_b32 s2, v237, 53
	s_cselect_b64 s[0:1], -1, 0
	v_readlane_b32 s3, v237, 54
	s_and_b64 s[2:3], s[0:1], s[2:3]
	s_add_i32 s0, s4, 0xfffff900
	s_cmpk_lt_i32 s0, 0x1000
	s_cselect_b64 s[4:5], -1, 0
	s_and_b64 s[2:3], s[2:3], s[4:5]
	s_andn2_b64 vcc, exec, s[2:3]
	v_mbcnt_lo_u32_b32 v2, -1, 0
	v_mbcnt_hi_u32_b32 v2, -1, v2
	s_cbranch_vccnz .LBB0_278
	v_and_b32_e32 v0, 7, v2
	v_lshlrev_b32_e32 v4, 4, v0
	s_waitcnt lgkmcnt(0)
	v_mov_b32_e32 v5, 0
	s_lshl_b32 s1, s93, 14
	v_ashrrev_i32_e32 v21, 3, v2
	v_mul_u32_u24_e32 v3, 0x420, v0
	v_lshl_add_u64 v[0:1], s[78:79], 0, v[4:5]
	s_mov_b64 s[2:3], 0x25100000
	s_add_i32 s4, s1, 0
	v_ashrrev_i32_e32 v20, 5, v2
	v_lshl_add_u64 v[0:1], v[0:1], 0, s[2:3]
	v_lshlrev_b32_e32 v4, 2, v21
	s_movk_i32 s2, 0x84
	v_add3_u32 v22, s4, v3, v4
	v_mul_lo_u32 v3, v20, s2
	v_lshlrev_b32_e32 v2, 2, v2
	v_readlane_b32 s16, v237, 35
	v_add_u32_e32 v3, s1, v3
	v_and_b32_e32 v4, 0x7c, v2
	v_readlane_b32 s22, v237, 41
	v_readlane_b32 s23, v237, 42
	s_mov_b32 s5, 0
	v_add3_u32 v23, v3, v4, 0
	v_lshl_add_u64 v[2:3], s[22:23], 0, v[4:5]
	v_add_u32_e32 v24, 14, v20
	v_add_u32_e32 v25, 12, v20
	v_add_u32_e32 v26, 10, v20
	v_add_u32_e32 v27, 8, v20
	v_add_u32_e32 v28, 6, v20
	v_add_u32_e32 v29, 4, v20
	v_add_u32_e32 v30, 2, v20
	v_readlane_b32 s17, v237, 36
	v_readlane_b32 s18, v237, 37
	v_readlane_b32 s19, v237, 38
	v_readlane_b32 s20, v237, 39
	v_readlane_b32 s21, v237, 40
	v_readlane_b32 s24, v237, 43
	v_readlane_b32 s25, v237, 44
	v_readlane_b32 s26, v237, 45
	v_readlane_b32 s27, v237, 46
	v_readlane_b32 s28, v237, 47
	v_readlane_b32 s29, v237, 48
	v_readlane_b32 s30, v237, 49
	v_readlane_b32 s31, v237, 50
	s_movk_i32 s1, 0x1000
	v_writelane_b32 v236, s1, 62
	s_branch .LBB0_272
.LBB0_271:
	s_add_i32 s0, s0, 0x100
	v_readlane_b32 s1, v236, 62
	s_cmp_lt_i32 s0, s1
	s_cbranch_scc1 .LBB0_272
	s_cmpk_eq_i32 s1, 0x1000
	s_cbranch_scc0 .LBB0_278
	v_readlane_b32 s2, v237, 27
	v_readlane_b32 s3, v237, 28
	v_readlane_b32 s6, v237, 41
	v_readlane_b32 s7, v237, 42
	s_sub_u32 s2, s2, s6
	s_subb_u32 s3, s3, s7
	v_lshl_add_u64 v[2:3], v[2:3], 0, s[2:3]
	s_mov_b32 s2, 0xf6000000
	s_mov_b32 s3, -1
	v_lshl_add_u64 v[0:1], v[0:1], 0, s[2:3]
	s_lshl_b32 s0, s84, 3
	s_add_i32 s0, s0, s93
	s_add_i32 s0, s0, 0xfffff900
	s_movk_i32 s1, 0x2000
	v_writelane_b32 v236, s1, 62
	s_branch .LBB0_272

; #define LAS __attribute__((address_space(3)))
; #define LDS_WAIT() asm volatile("s_waitcnt lgkmcnt(0)" ::: "memory")
; __device__ __forceinline__ unsigned cvt_pk_bf16(float lo, float hi) { const f32x2 v = {lo, hi}; const bf16x2_t b = __builtin_convertvector(v, bf16x2_t); return __builtin_bit_cast(unsigned, b); }
; __device__ __forceinline__ void p0_item(const float* __restrict__ W, int ldw, int K, bf16_t* __restrict__ WT, int sc, int dn, int k0, const float* __restrict__ gk, LAS float* scr, int lane) {
;     ...
; #pragma unroll 8
;     for (int i = 0; i < 32; ++i) { const int kk = 2 * i + (lane >> 5); float v = __builtin_nontemporal_load(W + (size_t)(k0 + kk) * ldw + sc + (lane & 31)); if (gk) v *= gk[k0 + kk]; scr[kk * 33 + (lane & 31)] = v; }
;     LDS_WAIT(); asm volatile("" ::: "memory");
; #pragma unroll
;     for (int j = 0; j < 4; ++j) { const int n = (lane >> 3) + 8 * j; const LAS float* s = scr + (8 * c) * 33 + n;
;         u32x4 o; o.x = cvt_pk_bf16(s[0 * 33], s[1 * 33]); o.y = cvt_pk_bf16(s[2 * 33], s[3 * 33]); o.z = cvt_pk_bf16(s[4 * 33], s[5 * 33]); o.w = cvt_pk_bf16(s[6 * 33], s[7 * 33]);
;         __builtin_nontemporal_store(o, (u32x4*)(WT + (size_t)(dn + n) * K + k0 + 8 * c)); }
;     LDS_WAIT(); asm volatile("" ::: "memory");
.LBB0_274:
	v_lshl_add_u64 v[32:33], v[18:19], 0, s[6:7]
	v_lshl_add_u64 v[34:35], v[16:17], 0, s[6:7]
	v_lshl_add_u64 v[36:37], v[14:15], 0, s[6:7]
	v_lshl_add_u64 v[38:39], v[12:13], 0, s[6:7]
	v_lshl_add_u64 v[40:41], v[10:11], 0, s[6:7]
	v_lshl_add_u64 v[42:43], v[8:9], 0, s[6:7]
	v_lshl_add_u64 v[44:45], v[6:7], 0, s[6:7]
	v_lshl_add_u64 v[46:47], v[4:5], 0, s[6:7]
	global_load_dword v176, v[32:33], off nt
	global_load_dword v177, v[34:35], off nt
	global_load_dword v178, v[36:37], off nt
	global_load_dword v179, v[38:39], off nt
	global_load_dword v180, v[40:41], off nt
	global_load_dword v181, v[42:43], off nt
	global_load_dword v182, v[44:45], off nt
	global_load_dword v183, v[46:47], off nt
	s_add_u32 s6, s6, 0x40000
	s_addc_u32 s7, s7, 0
	v_lshl_add_u64 v[32:33], v[18:19], 0, s[6:7]
	v_lshl_add_u64 v[34:35], v[16:17], 0, s[6:7]
	v_lshl_add_u64 v[36:37], v[14:15], 0, s[6:7]
	v_lshl_add_u64 v[38:39], v[12:13], 0, s[6:7]
	v_lshl_add_u64 v[40:41], v[10:11], 0, s[6:7]
	v_lshl_add_u64 v[42:43], v[8:9], 0, s[6:7]
	v_lshl_add_u64 v[44:45], v[6:7], 0, s[6:7]
	v_lshl_add_u64 v[46:47], v[4:5], 0, s[6:7]
	global_load_dword v184, v[32:33], off nt
	global_load_dword v185, v[34:35], off nt
	global_load_dword v186, v[36:37], off nt
	global_load_dword v187, v[38:39], off nt
	global_load_dword v188, v[40:41], off nt
	global_load_dword v189, v[42:43], off nt
	global_load_dword v190, v[44:45], off nt
	global_load_dword v191, v[46:47], off nt
	s_add_u32 s6, s6, 0x40000
	s_addc_u32 s7, s7, 0
	v_lshl_add_u64 v[32:33], v[18:19], 0, s[6:7]
	v_lshl_add_u64 v[34:35], v[16:17], 0, s[6:7]
	v_lshl_add_u64 v[36:37], v[14:15], 0, s[6:7]
	v_lshl_add_u64 v[38:39], v[12:13], 0, s[6:7]
	v_lshl_add_u64 v[40:41], v[10:11], 0, s[6:7]
	v_lshl_add_u64 v[42:43], v[8:9], 0, s[6:7]
	v_lshl_add_u64 v[44:45], v[6:7], 0, s[6:7]
	v_lshl_add_u64 v[46:47], v[4:5], 0, s[6:7]
	global_load_dword v192, v[32:33], off nt
	global_load_dword v193, v[34:35], off nt
	global_load_dword v194, v[36:37], off nt
	global_load_dword v195, v[38:39], off nt
	global_load_dword v196, v[40:41], off nt
	global_load_dword v197, v[42:43], off nt
	global_load_dword v198, v[44:45], off nt
	global_load_dword v199, v[46:47], off nt
	s_add_u32 s6, s6, 0x40000
	s_addc_u32 s7, s7, 0
	v_lshl_add_u64 v[32:33], v[18:19], 0, s[6:7]
	v_lshl_add_u64 v[34:35], v[16:17], 0, s[6:7]
	v_lshl_add_u64 v[36:37], v[14:15], 0, s[6:7]
	v_lshl_add_u64 v[38:39], v[12:13], 0, s[6:7]
	v_lshl_add_u64 v[40:41], v[10:11], 0, s[6:7]
	v_lshl_add_u64 v[42:43], v[8:9], 0, s[6:7]
	v_lshl_add_u64 v[44:45], v[6:7], 0, s[6:7]
	v_lshl_add_u64 v[46:47], v[4:5], 0, s[6:7]
	global_load_dword v200, v[32:33], off nt
	global_load_dword v201, v[34:35], off nt
	global_load_dword v202, v[36:37], off nt
	global_load_dword v203, v[38:39], off nt
	global_load_dword v204, v[40:41], off nt
	global_load_dword v205, v[42:43], off nt
	global_load_dword v206, v[44:45], off nt
	global_load_dword v207, v[46:47], off nt
	s_add_u32 s6, s6, 0x40000
	s_addc_u32 s7, s7, 0
	v_add_u32_e32 v40, 0x400, v31
	s_waitcnt vmcnt(30)
	ds_write2_b32 v31, v176, v177 offset1:66
	s_waitcnt vmcnt(28)
	ds_write2_b32 v31, v178, v179 offset0:132 offset1:198
	s_waitcnt vmcnt(26)
	ds_write2_b32 v40, v180, v181 offset0:8 offset1:74
	s_waitcnt vmcnt(24)
	ds_write2_b32 v40, v182, v183 offset0:140 offset1:206
	v_add_u32_e32 v31, 0x840, v31
	v_add_u32_e32 v40, 0x400, v31
	s_waitcnt vmcnt(22)
	ds_write2_b32 v31, v184, v185 offset1:66
	s_waitcnt vmcnt(20)
	ds_write2_b32 v31, v186, v187 offset0:132 offset1:198
	s_waitcnt vmcnt(18)
	ds_write2_b32 v40, v188, v189 offset0:8 offset1:74
	s_waitcnt vmcnt(16)
	ds_write2_b32 v40, v190, v191 offset0:140 offset1:206
	v_add_u32_e32 v31, 0x840, v31
	v_add_u32_e32 v40, 0x400, v31
	s_waitcnt vmcnt(14)
	ds_write2_b32 v31, v192, v193 offset1:66
	s_waitcnt vmcnt(12)
	ds_write2_b32 v31, v194, v195 offset0:132 offset1:198
	s_waitcnt vmcnt(10)
	ds_write2_b32 v40, v196, v197 offset0:8 offset1:74
	s_waitcnt vmcnt(8)
	ds_write2_b32 v40, v198, v199 offset0:140 offset1:206
	v_add_u32_e32 v31, 0x840, v31
	v_add_u32_e32 v40, 0x400, v31
	s_waitcnt vmcnt(6)
	ds_write2_b32 v31, v200, v201 offset1:66
	s_waitcnt vmcnt(4)
	ds_write2_b32 v31, v202, v203 offset0:132 offset1:198
	s_waitcnt vmcnt(2)
	ds_write2_b32 v40, v204, v205 offset0:8 offset1:74
	s_waitcnt vmcnt(0)
	ds_write2_b32 v40, v206, v207 offset0:140 offset1:206
	v_add_u32_e32 v31, 0x840, v31
	s_waitcnt lgkmcnt(0)
	ds_read2_b32 v[8:9], v22 offset0:33 offset1:41
	ds_read2_b32 v[10:11], v22 offset1:8
	ds_read2_b32 v[12:13], v22 offset0:66 offset1:74
	ds_read2_b32 v[14:15], v22 offset0:99 offset1:107
	ds_read2_b32 v[16:17], v22 offset0:132 offset1:140
	ds_read2_b32 v[18:19], v22 offset0:165 offset1:173
	ds_read2_b32 v[32:33], v22 offset0:198 offset1:206
	ds_read2_b32 v[34:35], v22 offset0:231 offset1:239
	v_add_u32_e32 v38, s4, v21
	s_ashr_i32 s3, s2, 31
	v_ashrrev_i32_e32 v39, 31, v38
	v_lshl_add_u64 v[36:37], s[2:3], 1, v[0:1]
	v_lshlrev_b64 v[40:41], 13, v[38:39]
	s_waitcnt lgkmcnt(6)
	v_cvt_pk_bf16_f32 v4, v10, v8
	s_waitcnt lgkmcnt(4)
	v_cvt_pk_bf16_f32 v5, v12, v14
	s_waitcnt lgkmcnt(2)
	v_cvt_pk_bf16_f32 v6, v16, v18
	s_waitcnt lgkmcnt(0)
	v_cvt_pk_bf16_f32 v7, v32, v34
	v_lshl_add_u64 v[40:41], v[36:37], 0, v[40:41]
	v_add_u32_e32 v8, 8, v38
	global_store_dwordx4 v[40:41], v[4:7], off nt
	s_nop 1
	v_cvt_pk_bf16_f32 v4, v11, v9
	v_ashrrev_i32_e32 v9, 31, v8
	v_cvt_pk_bf16_f32 v5, v13, v15
	v_cvt_pk_bf16_f32 v6, v17, v19
	v_cvt_pk_bf16_f32 v7, v33, v35
	v_lshlrev_b64 v[8:9], 13, v[8:9]
	ds_read2_b32 v[10:11], v22 offset0:49 offset1:57
	ds_read2_b32 v[12:13], v22 offset0:16 offset1:24
	ds_read2_b32 v[14:15], v22 offset0:82 offset1:90
	ds_read2_b32 v[16:17], v22 offset0:115 offset1:123
	ds_read2_b32 v[18:19], v22 offset0:148 offset1:156
	ds_read2_b32 v[32:33], v22 offset0:181 offset1:189
	ds_read2_b32 v[34:35], v22 offset0:214 offset1:222
	ds_read2_b32 v[40:41], v22 offset0:247 offset1:255
	v_lshl_add_u64 v[8:9], v[36:37], 0, v[8:9]
	global_store_dwordx4 v[8:9], v[4:7], off nt
	v_add_u32_e32 v8, 16, v38
	v_ashrrev_i32_e32 v9, 31, v8
	v_lshlrev_b64 v[8:9], 13, v[8:9]
	s_waitcnt lgkmcnt(6)
	v_cvt_pk_bf16_f32 v4, v12, v10
	s_waitcnt lgkmcnt(4)
	v_cvt_pk_bf16_f32 v5, v14, v16
	s_waitcnt lgkmcnt(2)
	v_cvt_pk_bf16_f32 v6, v18, v32
	s_waitcnt lgkmcnt(0)
	v_cvt_pk_bf16_f32 v7, v34, v40
	v_lshl_add_u64 v[8:9], v[36:37], 0, v[8:9]
	global_store_dwordx4 v[8:9], v[4:7], off nt
	v_add_u32_e32 v8, 24, v38
	v_ashrrev_i32_e32 v9, 31, v8
	v_lshlrev_b64 v[8:9], 13, v[8:9]
	v_cvt_pk_bf16_f32 v4, v13, v11
	v_cvt_pk_bf16_f32 v5, v15, v17
	v_cvt_pk_bf16_f32 v6, v19, v33
	v_cvt_pk_bf16_f32 v7, v35, v41
	v_lshl_add_u64 v[8:9], v[36:37], 0, v[8:9]
	global_store_dwordx4 v[8:9], v[4:7], off nt
	s_waitcnt lgkmcnt(0)
	s_branch .LBB0_271

; #define CONV_WCO(lo_, hi_, w_, nw_) do { LAS float* scr_ = (LAS float*)(lds + wave * 16384); for (int r = (lo_) + (w_); r < (hi_); r += (nw_)) { const int nblk = 4096 / 32, kb = r / nblk, nb = r % nblk; \
;         p0_item(in_w_co, 4096, 4096, Wco_t, nb * 32, nb * 32, kb * 64, nullptr, scr_, lane); } } while (0)
; #define CONV_WFI2(w_, nw_) do { LAS float* scr_ = (LAS float*)(lds + wave * 16384); for (int r = I_FI / 2 + (w_); r < I_FI; r += (nw_)) { const int nblk = DFF2 / 32, kb = r / nblk, nb = r % nblk; \
;         p0_item_ln(in_w_ffn_in, DFF2, D, Wfi_t, wfi_src(nb), nb * 32, kb * 64, in_ln2_g, in_ln2_b, S2V, C2V, scr_, lane); } } while (0)
; __global__ void __launch_bounds__(NWAVES * 64, 2) mk_fwd(Args args) {
;     ...
;         else if (bx >= 128) { if (split) { CONV_WFI2((bx - 128) * NWAVES + wave, 128 * NWAVES); CONV_WCO(I_SQ / 2, I_SQ, (bx - 128) * NWAVES + wave, 128 * NWAVES); } }
.LBB0_922:
	s_and_b64 vcc, exec, s[2:3]
	s_cbranch_vccz .LBB0_940
	v_readlane_b32 s2, v237, 53
	v_readlane_b32 s3, v237, 54
	s_andn2_b64 vcc, exec, s[2:3]
	s_cbranch_vccnz .LBB0_940
	s_add_i32 s31, s93, s22
	s_lshl_b32 s22, s93, 14
	s_add_i32 s23, s22, 0
	s_addk_i32 s31, 0xfc00
	s_cmpk_gt_i32 s31, 0x55ff
	v_ashrrev_i32_e32 v16, 5, v136
	v_and_b32_e32 v36, 7, v136
	v_ashrrev_i32_e32 v34, 3, v136
	v_lshlrev_b32_e32 v35, 2, v136
	s_cbranch_scc1 .LBB0_931
	v_readlane_b32 s52, v237, 35
	v_readlane_b32 s56, v237, 39
	v_readlane_b32 s57, v237, 40
	v_readlane_b32 s58, v237, 41
	v_readlane_b32 s59, v237, 42
	v_readlane_b32 s60, v237, 43
	v_readlane_b32 s61, v237, 44
	v_readlane_b32 s62, v237, 45
	v_readlane_b32 s63, v237, 46
	v_readlane_b32 s64, v237, 47
	v_readlane_b32 s65, v237, 48
	v_readlane_b32 s66, v237, 49
	v_readlane_b32 s67, v237, 50
	s_mov_b64 s[56:57], s[60:61]
	v_lshlrev_b32_e32 v0, 5, v36
	s_waitcnt lgkmcnt(0)
	v_mov_b32_e32 v1, 0
	s_mov_b64 s[58:59], s[62:63]
	v_lshl_add_u64 v[18:19], s[56:57], 0, v[0:1]
	v_lshl_add_u64 v[20:21], s[58:59], 0, v[0:1]
	v_lshlrev_b32_e32 v0, 4, v36
	v_lshl_add_u64 v[2:3], s[78:79], 0, v[0:1]
	s_mov_b64 s[2:3], 0xaf00000
	v_lshl_add_u64 v[22:23], v[2:3], 0, s[2:3]
	v_lshl_add_u32 v2, v36, 3, v34
	v_ashrrev_i32_e32 v3, 31, v2
	v_lshl_add_u64 v[2:3], v[2:3], 2, s[78:79]
	s_mov_b64 s[10:11], 0x58000
	v_lshl_add_u64 v[24:25], v[2:3], 0, s[10:11]
	s_mov_b64 s[10:11], 0x70000
	v_mul_u32_u24_e32 v4, 0x420, v36
	v_lshlrev_b32_e32 v0, 2, v34
	v_lshl_add_u64 v[26:27], v[2:3], 0, s[10:11]
	s_movk_i32 s10, 0x84
	v_add3_u32 v37, s23, v4, v0
	v_mul_lo_u32 v0, v16, s10
	s_mov_b64 s[60:61], s[64:65]
	v_add_u32_e32 v2, s22, v0
	v_and_b32_e32 v0, 0x7c, v35
	v_add3_u32 v38, v2, v0, 0
	v_lshl_add_u64 v[28:29], s[60:61], 0, v[0:1]
	v_mbcnt_lo_u32_b32 v0, -1, 0
	v_mbcnt_hi_u32_b32 v46, -1, v0
	v_and_b32_e32 v0, 64, v46
	s_add_i32 s33, s31, 0x4000
	v_cmp_gt_u32_e32 vcc, 4, v36
	v_cmp_eq_u32_e64 s[2:3], 3, v36
	v_cmp_eq_u32_e64 s[4:5], 2, v36
	v_cmp_eq_u32_e64 s[6:7], 1, v36
	v_cmp_eq_u32_e64 s[8:9], 0, v36
	v_add_u32_e32 v39, 14, v16
	v_add_u32_e32 v40, 12, v16
	v_add_u32_e32 v41, 10, v16
	v_add_u32_e32 v42, 8, v16
	v_add_u32_e32 v43, 6, v16
	v_add_u32_e32 v44, 4, v16
	v_add_u32_e32 v45, 2, v16
	v_ashrrev_i32_e32 v17, 31, v16
	s_mov_b32 s35, 0x15800
	v_xor_b32_e32 v47, 1, v46
	v_add_u32_e32 v48, 64, v0
	v_xor_b32_e32 v49, 2, v46
	v_xor_b32_e32 v50, 4, v46
	v_readlane_b32 s53, v237, 36
	v_readlane_b32 s54, v237, 37
	v_readlane_b32 s55, v237, 38
	s_mov_b64 s[62:63], s[66:67]
	s_branch .LBB0_927

; #define LAS __attribute__((address_space(3)))
; #define LDS_WAIT() asm volatile("s_waitcnt lgkmcnt(0)" ::: "memory")
; __device__ __forceinline__ unsigned cvt_pk_bf16(float lo, float hi) { const f32x2 v = {lo, hi}; const bf16x2_t b = __builtin_convertvector(v, bf16x2_t); return __builtin_bit_cast(unsigned, b); }
; __device__ __forceinline__ void p0_item_ln(const float* __restrict__ W, int ldw, int K, bf16_t* __restrict__ WT, int sc, int dn, int k0, const float* __restrict__ gk, const float* __restrict__ bk,
;                                            float* sv, float* cv, LAS float* scr, int lane) {
;     ...
; #pragma unroll 8
;     for (int i = 0; i < 32; ++i) { const int kk = 2 * i + (lane >> 5); scr[kk * 33 + (lane & 31)] = __builtin_nontemporal_load(W + (size_t)(k0 + kk) * ldw + sc + (lane & 31)); }
;     const f32x4 ga = *(const f32x4*)(gk + k0 + 8 * c), gb = *(const f32x4*)(gk + k0 + 8 * c + 4), ba = *(const f32x4*)(bk + k0 + 8 * c), bb = *(const f32x4*)(bk + k0 + 8 * c + 4);
;     LDS_WAIT(); asm volatile("" ::: "memory");
;     float sk = 0.f, ck = 0.f;
; #pragma unroll
;     for (int j = 0; j < 4; ++j) { const int n = (lane >> 3) + 8 * j; const LAS float* sp = scr + (8 * c) * 33 + n;
;         const float w0 = sp[0 * 33], w1 = sp[1 * 33], w2 = sp[2 * 33], w3 = sp[3 * 33], w4 = sp[4 * 33], w5 = sp[5 * 33], w6 = sp[6 * 33], w7 = sp[7 * 33];
;         u32x4 o; o.x = cvt_pk_bf16(w0 * ga[0], w1 * ga[1]); o.y = cvt_pk_bf16(w2 * ga[2], w3 * ga[3]); o.z = cvt_pk_bf16(w4 * gb[0], w5 * gb[1]); o.w = cvt_pk_bf16(w6 * gb[2], w7 * gb[3]);
.LBB0_928:
	v_lshl_add_u64 v[32:33], v[14:15], 0, s[28:29]
	v_lshl_add_u64 v[52:53], v[12:13], 0, s[28:29]
	v_lshl_add_u64 v[54:55], v[10:11], 0, s[28:29]
	v_lshl_add_u64 v[56:57], v[8:9], 0, s[28:29]
	v_lshl_add_u64 v[58:59], v[6:7], 0, s[28:29]
	v_lshl_add_u64 v[60:61], v[4:5], 0, s[28:29]
	v_lshl_add_u64 v[62:63], v[2:3], 0, s[28:29]
	v_lshl_add_u64 v[64:65], v[0:1], 0, s[28:29]
	global_load_dword v176, v[32:33], off nt
	global_load_dword v177, v[52:53], off nt
	global_load_dword v178, v[54:55], off nt
	global_load_dword v179, v[56:57], off nt
	global_load_dword v180, v[58:59], off nt
	global_load_dword v181, v[60:61], off nt
	global_load_dword v182, v[62:63], off nt
	global_load_dword v183, v[64:65], off nt
	s_add_u32 s28, s28, 0x158000
	s_addc_u32 s29, s29, 0
	v_lshl_add_u64 v[32:33], v[14:15], 0, s[28:29]
	v_lshl_add_u64 v[52:53], v[12:13], 0, s[28:29]
	v_lshl_add_u64 v[54:55], v[10:11], 0, s[28:29]
	v_lshl_add_u64 v[56:57], v[8:9], 0, s[28:29]
	v_lshl_add_u64 v[58:59], v[6:7], 0, s[28:29]
	v_lshl_add_u64 v[60:61], v[4:5], 0, s[28:29]
	v_lshl_add_u64 v[62:63], v[2:3], 0, s[28:29]
	v_lshl_add_u64 v[64:65], v[0:1], 0, s[28:29]
	global_load_dword v184, v[32:33], off nt
	global_load_dword v185, v[52:53], off nt
	global_load_dword v186, v[54:55], off nt
	global_load_dword v187, v[56:57], off nt
	global_load_dword v188, v[58:59], off nt
	global_load_dword v189, v[60:61], off nt
	global_load_dword v190, v[62:63], off nt
	global_load_dword v191, v[64:65], off nt
	s_add_u32 s28, s28, 0x158000
	s_addc_u32 s29, s29, 0
	v_lshl_add_u64 v[32:33], v[14:15], 0, s[28:29]
	v_lshl_add_u64 v[52:53], v[12:13], 0, s[28:29]
	v_lshl_add_u64 v[54:55], v[10:11], 0, s[28:29]
	v_lshl_add_u64 v[56:57], v[8:9], 0, s[28:29]
	v_lshl_add_u64 v[58:59], v[6:7], 0, s[28:29]
	v_lshl_add_u64 v[60:61], v[4:5], 0, s[28:29]
	v_lshl_add_u64 v[62:63], v[2:3], 0, s[28:29]
	v_lshl_add_u64 v[64:65], v[0:1], 0, s[28:29]
	global_load_dword v192, v[32:33], off nt
	global_load_dword v193, v[52:53], off nt
	global_load_dword v194, v[54:55], off nt
	global_load_dword v195, v[56:57], off nt
	global_load_dword v196, v[58:59], off nt
	global_load_dword v197, v[60:61], off nt
	global_load_dword v198, v[62:63], off nt
	global_load_dword v199, v[64:65], off nt
	s_add_u32 s28, s28, 0x158000
	s_addc_u32 s29, s29, 0
	v_lshl_add_u64 v[32:33], v[14:15], 0, s[28:29]
	v_lshl_add_u64 v[52:53], v[12:13], 0, s[28:29]
	v_lshl_add_u64 v[54:55], v[10:11], 0, s[28:29]
	v_lshl_add_u64 v[56:57], v[8:9], 0, s[28:29]
	v_lshl_add_u64 v[58:59], v[6:7], 0, s[28:29]
	v_lshl_add_u64 v[60:61], v[4:5], 0, s[28:29]
	v_lshl_add_u64 v[62:63], v[2:3], 0, s[28:29]
	v_lshl_add_u64 v[64:65], v[0:1], 0, s[28:29]
	global_load_dword v200, v[32:33], off nt
	global_load_dword v201, v[52:53], off nt
	global_load_dword v202, v[54:55], off nt
	global_load_dword v203, v[56:57], off nt
	global_load_dword v204, v[58:59], off nt
	global_load_dword v205, v[60:61], off nt
	global_load_dword v206, v[62:63], off nt
	global_load_dword v207, v[64:65], off nt
	s_add_u32 s28, s28, 0x158000
	s_addc_u32 s29, s29, 0
	v_add_u32_e32 v56, 0x400, v30
	s_waitcnt vmcnt(30)
	ds_write2_b32 v30, v176, v177 offset1:66
	s_waitcnt vmcnt(28)
	ds_write2_b32 v30, v178, v179 offset0:132 offset1:198
	s_waitcnt vmcnt(26)
	ds_write2_b32 v56, v180, v181 offset0:8 offset1:74
	s_waitcnt vmcnt(24)
	ds_write2_b32 v56, v182, v183 offset0:140 offset1:206
	v_add_u32_e32 v30, 0x840, v30
	v_add_u32_e32 v56, 0x400, v30
	s_waitcnt vmcnt(22)
	ds_write2_b32 v30, v184, v185 offset1:66
	s_waitcnt vmcnt(20)
	ds_write2_b32 v30, v186, v187 offset0:132 offset1:198
	s_waitcnt vmcnt(18)
	ds_write2_b32 v56, v188, v189 offset0:8 offset1:74
	s_waitcnt vmcnt(16)
	ds_write2_b32 v56, v190, v191 offset0:140 offset1:206
	v_add_u32_e32 v30, 0x840, v30
	v_add_u32_e32 v56, 0x400, v30
	s_waitcnt vmcnt(14)
	ds_write2_b32 v30, v192, v193 offset1:66
	s_waitcnt vmcnt(12)
	ds_write2_b32 v30, v194, v195 offset0:132 offset1:198
	s_waitcnt vmcnt(10)
	ds_write2_b32 v56, v196, v197 offset0:8 offset1:74
	s_waitcnt vmcnt(8)
	ds_write2_b32 v56, v198, v199 offset0:140 offset1:206
	v_add_u32_e32 v30, 0x840, v30
	v_add_u32_e32 v56, 0x400, v30
	s_waitcnt vmcnt(6)
	ds_write2_b32 v30, v200, v201 offset1:66
	s_waitcnt vmcnt(4)
	ds_write2_b32 v30, v202, v203 offset0:132 offset1:198
	s_waitcnt vmcnt(2)
	ds_write2_b32 v56, v204, v205 offset0:8 offset1:74
	s_waitcnt vmcnt(0)
	ds_write2_b32 v56, v206, v207 offset0:140 offset1:206
	v_add_u32_e32 v30, 0x840, v30
	s_lshl_b64 s[28:29], s[10:11], 2
	v_lshl_add_u64 v[0:1], v[18:19], 0, s[28:29]
	global_load_dwordx4 v[12:15], v[0:1], off
	global_load_dwordx4 v[8:11], v[0:1], off offset:16
	v_lshl_add_u64 v[0:1], v[20:21], 0, s[28:29]
	global_load_dwordx4 v[4:7], v[0:1], off
	s_nop 0
	global_load_dwordx4 v[0:3], v[0:1], off offset:16
	s_waitcnt lgkmcnt(0)
	v_lshl_add_u64 v[30:31], s[10:11], 1, v[22:23]
	v_cmp_lt_i32_e64 s[10:11], v47, v48
	ds_read2_b32 v[60:61], v37 offset1:8
	ds_read2_b32 v[62:63], v37 offset0:33 offset1:41
	ds_read2_b32 v[64:65], v37 offset0:66 offset1:74
	ds_read2_b32 v[66:67], v37 offset0:99 offset1:107
	ds_read2_b32 v[68:69], v37 offset0:132 offset1:140
	ds_read2_b32 v[70:71], v37 offset0:165 offset1:173
	ds_read2_b32 v[72:73], v37 offset0:198 offset1:206
	ds_read2_b32 v[74:75], v37 offset0:231 offset1:239
	v_cndmask_b32_e64 v33, v46, v47, s[10:11]
	v_cmp_lt_i32_e64 s[10:11], v49, v48
	v_add_u32_e32 v32, s20, v34
	v_lshlrev_b32_e32 v84, 2, v33
	v_cndmask_b32_e64 v51, v46, v49, s[10:11]
	v_cmp_lt_i32_e64 s[10:11], v50, v48
	v_ashrrev_i32_e32 v33, 31, v32
	s_waitcnt lgkmcnt(5)
; #define LAS __attribute__((address_space(3)))
; __device__ __forceinline__ unsigned cvt_pk_bf16(float lo, float hi) { const f32x2 v = {lo, hi}; const bf16x2_t b = __builtin_convertvector(v, bf16x2_t); return __builtin_bit_cast(unsigned, b); }
; __device__ __forceinline__ float bf_lo(unsigned w) { return __uint_as_float(w << 16); }
; __device__ __forceinline__ float bf_hi(unsigned w) { return __uint_as_float(w & 0xffff0000u); }
; __device__ __forceinline__ void p0_item_ln(const float* __restrict__ W, int ldw, int K, bf16_t* __restrict__ WT, int sc, int dn, int k0, const float* __restrict__ gk, const float* __restrict__ bk,
;                                            float* sv, float* cv, LAS float* scr, int lane) {
;     ...
;     for (int j = 0; j < 4; ++j) { const int n = (lane >> 3) + 8 * j; const LAS float* sp = scr + (8 * c) * 33 + n;
;         const float w0 = sp[0 * 33], w1 = sp[1 * 33], w2 = sp[2 * 33], w3 = sp[3 * 33], w4 = sp[4 * 33], w5 = sp[5 * 33], w6 = sp[6 * 33], w7 = sp[7 * 33];
;         u32x4 o; o.x = cvt_pk_bf16(w0 * ga[0], w1 * ga[1]); o.y = cvt_pk_bf16(w2 * ga[2], w3 * ga[3]); o.z = cvt_pk_bf16(w4 * gb[0], w5 * gb[1]); o.w = cvt_pk_bf16(w6 * gb[2], w7 * gb[3]);
;         __builtin_nontemporal_store(o, (u32x4*)(WT + (size_t)(dn + n) * K + k0 + 8 * c));
;         float ss = ((bf_lo(o.x) + bf_hi(o.x)) + (bf_lo(o.y) + bf_hi(o.y))) + ((bf_lo(o.z) + bf_hi(o.z)) + (bf_lo(o.w) + bf_hi(o.w)));
;         float cs = ((w0 * ba[0] + w1 * ba[1]) + (w2 * ba[2] + w3 * ba[3])) + ((w4 * bb[0] + w5 * bb[1]) + (w6 * bb[2] + w7 * bb[3]));
;         ss += __shfl_xor(ss, 1); ss += __shfl_xor(ss, 2); ss += __shfl_xor(ss, 4); cs += __shfl_xor(cs, 1); cs += __shfl_xor(cs, 2); cs += __shfl_xor(cs, 4);
	v_mov_b32_e32 v54, v64
	v_cndmask_b32_e64 v52, v46, v50, s[10:11]
	v_lshlrev_b32_e32 v86, 2, v52
	v_lshlrev_b64 v[52:53], 13, v[32:33]
	v_lshl_add_u64 v[56:57], v[30:31], 0, v[52:53]
	v_mov_b32_e32 v52, v60
	v_mov_b32_e32 v53, v62
	s_waitcnt lgkmcnt(4)
	v_mov_b32_e32 v55, v66
	s_waitcnt lgkmcnt(3)
	v_mov_b32_e32 v76, v68
	s_waitcnt lgkmcnt(2)
	v_mov_b32_e32 v77, v70
	s_waitcnt lgkmcnt(1)
	v_mov_b32_e32 v78, v72
	s_waitcnt lgkmcnt(0)
	v_mov_b32_e32 v79, v74
	v_lshlrev_b32_e32 v85, 2, v51
	v_add_u32_e32 v58, 8, v32
	s_waitcnt vmcnt(3)
	v_pk_mul_f32 v[52:53], v[12:13], v[52:53]
	v_pk_mul_f32 v[54:55], v[14:15], v[54:55]
	s_waitcnt vmcnt(2)
	v_pk_mul_f32 v[76:77], v[8:9], v[76:77]
	v_pk_mul_f32 v[78:79], v[10:11], v[78:79]
	s_waitcnt vmcnt(1)
	v_mul_f32_e32 v33, v5, v62
	v_mul_f32_e32 v51, v7, v66
	s_waitcnt vmcnt(0)
	v_mul_f32_e32 v59, v1, v70
	v_mul_f32_e32 v87, v3, v74
	v_mov_b32_e32 v62, v61
	v_mov_b32_e32 v66, v65
	v_mov_b32_e32 v70, v69
	v_cvt_pk_bf16_f32 v52, v52, v53
	v_cvt_pk_bf16_f32 v53, v54, v55
	v_cvt_pk_bf16_f32 v54, v76, v77
	v_cvt_pk_bf16_f32 v55, v78, v79
	v_fmac_f32_e32 v33, v4, v60
	v_fmac_f32_e32 v51, v6, v64
	v_fmac_f32_e32 v59, v0, v68
	v_fmac_f32_e32 v87, v2, v72
	v_pk_mul_f32 v[76:77], v[12:13], v[62:63]
	v_pk_mul_f32 v[78:79], v[14:15], v[66:67]
	v_pk_mul_f32 v[80:81], v[8:9], v[70:71]
	global_store_dwordx4 v[56:57], v[52:55], off nt
	v_lshlrev_b32_e32 v60, 16, v52
	v_lshlrev_b32_e32 v62, 16, v53
	v_and_b32_e32 v52, 0xffff0000, v52
	v_and_b32_e32 v53, 0xffff0000, v53
	v_lshlrev_b32_e32 v64, 16, v54
	v_and_b32_e32 v66, 0xffff0000, v54
	v_lshlrev_b32_e32 v68, 16, v55
	v_and_b32_e32 v70, 0xffff0000, v55
	v_add_f32_e32 v33, v33, v51
	v_add_f32_e32 v51, v59, v87
	v_add_f32_e32 v52, v60, v52
	v_add_f32_e32 v53, v62, v53
	v_add_f32_e32 v59, v64, v66
	v_add_f32_e32 v60, v68, v70
	v_add_f32_e32 v33, v33, v51
	v_add_f32_e32 v51, v52, v53
	v_add_f32_e32 v52, v59, v60
	v_add_f32_e32 v51, v51, v52
	ds_bpermute_b32 v52, v84, v51
	v_cvt_pk_bf16_f32 v54, v76, v77
	v_cvt_pk_bf16_f32 v55, v78, v79
	v_lshlrev_b32_e32 v59, 16, v54
	v_and_b32_e32 v60, 0xffff0000, v54
	s_waitcnt lgkmcnt(0)
	v_add_f32_e32 v52, v51, v52
	ds_bpermute_b32 v62, v85, v52
	v_mov_b32_e32 v74, v73
	v_lshlrev_b32_e32 v64, 16, v55
	v_add_f32_e32 v59, v59, v60
	v_and_b32_e32 v60, 0xffff0000, v55
	v_pk_mul_f32 v[82:83], v[10:11], v[74:75]
	v_cvt_pk_bf16_f32 v56, v80, v81
	v_add_f32_e32 v60, v64, v60
	v_cvt_pk_bf16_f32 v57, v82, v83
	s_waitcnt lgkmcnt(0)
	v_add_f32_e32 v52, v52, v62
	v_add_f32_e32 v59, v59, v60
	v_lshlrev_b32_e32 v60, 16, v56
	v_and_b32_e32 v62, 0xffff0000, v56
	v_add_f32_e32 v60, v60, v62
	v_lshlrev_b32_e32 v62, 16, v57
	v_and_b32_e32 v64, 0xffff0000, v57
	v_add_f32_e32 v62, v62, v64
	v_add_f32_e32 v60, v60, v62
	v_add_f32_e32 v60, v59, v60
	v_mul_f32_e32 v59, v5, v63
	v_fmac_f32_e32 v59, v4, v61
	v_mul_f32_e32 v61, v7, v67
	v_fmac_f32_e32 v61, v6, v65
	v_add_f32_e32 v59, v59, v61
	v_mul_f32_e32 v61, v1, v71
	v_mul_f32_e32 v62, v3, v75
	v_fmac_f32_e32 v61, v0, v69
	v_fmac_f32_e32 v62, v2, v73
	v_add_f32_e32 v61, v61, v62
	v_add_f32_e32 v61, v59, v61
	ds_bpermute_b32 v62, v84, v60
	ds_bpermute_b32 v63, v84, v61
	v_ashrrev_i32_e32 v59, 31, v58
	v_lshlrev_b64 v[58:59], 13, v[58:59]
	v_lshl_add_u64 v[58:59], v[30:31], 0, v[58:59]
	s_waitcnt lgkmcnt(1)
	v_add_f32_e32 v60, v60, v62
	s_waitcnt lgkmcnt(0)
	v_add_f32_e32 v61, v61, v63
	ds_bpermute_b32 v62, v85, v60
	ds_bpermute_b32 v63, v85, v61
	global_store_dwordx4 v[58:59], v[54:57], off nt
	ds_bpermute_b32 v53, v84, v33
	s_waitcnt lgkmcnt(0)
	v_add_f32_e32 v33, v33, v53
	v_add_f32_e32 v56, v60, v62
	v_add_f32_e32 v54, v61, v63
	ds_read2_b32 v[62:63], v37 offset0:16 offset1:24
	ds_read2_b32 v[64:65], v37 offset0:49 offset1:57
	ds_read2_b32 v[66:67], v37 offset0:82 offset1:90
	ds_read2_b32 v[68:69], v37 offset0:115 offset1:123
	ds_read2_b32 v[70:71], v37 offset0:148 offset1:156
	ds_read2_b32 v[72:73], v37 offset0:181 offset1:189
	ds_read2_b32 v[74:75], v37 offset0:214 offset1:222
	ds_read2_b32 v[76:77], v37 offset0:247 offset1:255
	s_waitcnt lgkmcnt(7)
	v_mov_b32_e32 v58, v62
	s_waitcnt lgkmcnt(6)
	v_mov_b32_e32 v59, v64
	v_pk_mul_f32 v[58:59], v[12:13], v[58:59]
	s_waitcnt lgkmcnt(5)
	v_mov_b32_e32 v60, v66
	s_waitcnt lgkmcnt(4)
	v_mov_b32_e32 v61, v68
	v_cvt_pk_bf16_f32 v58, v58, v59
	v_pk_mul_f32 v[60:61], v[14:15], v[60:61]
	v_lshlrev_b32_e32 v80, 16, v58
	v_cvt_pk_bf16_f32 v59, v60, v61
	s_waitcnt lgkmcnt(3)
; #define LAS __attribute__((address_space(3)))
; __device__ __forceinline__ unsigned cvt_pk_bf16(float lo, float hi) { const f32x2 v = {lo, hi}; const bf16x2_t b = __builtin_convertvector(v, bf16x2_t); return __builtin_bit_cast(unsigned, b); }
; __device__ __forceinline__ float bf_lo(unsigned w) { return __uint_as_float(w << 16); }
; __device__ __forceinline__ float bf_hi(unsigned w) { return __uint_as_float(w & 0xffff0000u); }
; __device__ __forceinline__ void p0_item_ln(const float* __restrict__ W, int ldw, int K, bf16_t* __restrict__ WT, int sc, int dn, int k0, const float* __restrict__ gk, const float* __restrict__ bk,
;                                            float* sv, float* cv, LAS float* scr, int lane) {
;     ...
;     for (int j = 0; j < 4; ++j) { const int n = (lane >> 3) + 8 * j; const LAS float* sp = scr + (8 * c) * 33 + n;
;         const float w0 = sp[0 * 33], w1 = sp[1 * 33], w2 = sp[2 * 33], w3 = sp[3 * 33], w4 = sp[4 * 33], w5 = sp[5 * 33], w6 = sp[6 * 33], w7 = sp[7 * 33];
;         u32x4 o; o.x = cvt_pk_bf16(w0 * ga[0], w1 * ga[1]); o.y = cvt_pk_bf16(w2 * ga[2], w3 * ga[3]); o.z = cvt_pk_bf16(w4 * gb[0], w5 * gb[1]); o.w = cvt_pk_bf16(w6 * gb[2], w7 * gb[3]);
;         __builtin_nontemporal_store(o, (u32x4*)(WT + (size_t)(dn + n) * K + k0 + 8 * c));
;         float ss = ((bf_lo(o.x) + bf_hi(o.x)) + (bf_lo(o.y) + bf_hi(o.y))) + ((bf_lo(o.z) + bf_hi(o.z)) + (bf_lo(o.w) + bf_hi(o.w)));
;         float cs = ((w0 * ba[0] + w1 * ba[1]) + (w2 * ba[2] + w3 * ba[3])) + ((w4 * bb[0] + w5 * bb[1]) + (w6 * bb[2] + w7 * bb[3]));
;         ss += __shfl_xor(ss, 1); ss += __shfl_xor(ss, 2); ss += __shfl_xor(ss, 4); cs += __shfl_xor(cs, 1); cs += __shfl_xor(cs, 2); cs += __shfl_xor(cs, 4);
;         if (c == j) { sk = ss; ck = cs; } }
;     if (c < 4) { const int n = (lane >> 3) + 8 * c; atomicAdd(sv + dn + n, sk); atomicAdd(cv + dn + n, ck); }
	v_mov_b32_e32 v60, v70
	s_waitcnt lgkmcnt(2)
	v_mov_b32_e32 v61, v72
	v_and_b32_e32 v81, 0xffff0000, v58
	v_pk_mul_f32 v[60:61], v[8:9], v[60:61]
	s_waitcnt lgkmcnt(1)
	v_mov_b32_e32 v78, v74
	s_waitcnt lgkmcnt(0)
	v_mov_b32_e32 v79, v76
	v_add_f32_e32 v80, v80, v81
	v_lshlrev_b32_e32 v81, 16, v59
	v_and_b32_e32 v82, 0xffff0000, v59
	v_cvt_pk_bf16_f32 v60, v60, v61
	v_pk_mul_f32 v[78:79], v[10:11], v[78:79]
	v_add_f32_e32 v81, v81, v82
	v_cvt_pk_bf16_f32 v61, v78, v79
	v_add_f32_e32 v80, v80, v81
	v_lshlrev_b32_e32 v81, 16, v60
	v_and_b32_e32 v82, 0xffff0000, v60
	v_add_f32_e32 v81, v81, v82
	v_lshlrev_b32_e32 v82, 16, v61
	v_and_b32_e32 v83, 0xffff0000, v61
	v_add_f32_e32 v82, v82, v83
	v_add_f32_e32 v81, v81, v82
	v_mul_f32_e32 v64, v5, v64
	v_add_f32_e32 v80, v80, v81
	v_fmac_f32_e32 v64, v4, v62
	v_mul_f32_e32 v62, v7, v68
	v_fmac_f32_e32 v62, v6, v66
	ds_bpermute_b32 v66, v84, v80
	v_add_f32_e32 v62, v64, v62
	v_mul_f32_e32 v64, v1, v72
	v_mul_f32_e32 v68, v3, v76
	v_fmac_f32_e32 v64, v0, v70
	v_fmac_f32_e32 v68, v2, v74
	v_add_f32_e32 v64, v64, v68
	v_add_f32_e32 v62, v62, v64
	s_waitcnt lgkmcnt(0)
	v_add_f32_e32 v64, v80, v66
	ds_bpermute_b32 v66, v85, v64
	ds_bpermute_b32 v68, v84, v62
	v_add_u32_e32 v78, 16, v32
	v_ashrrev_i32_e32 v79, 31, v78
	v_lshlrev_b64 v[78:79], 13, v[78:79]
	v_lshl_add_u64 v[78:79], v[30:31], 0, v[78:79]
	global_store_dwordx4 v[78:79], v[58:61], off nt
	v_mov_b32_e32 v72, v71
	v_pk_mul_f32 v[8:9], v[8:9], v[72:73]
	s_waitcnt lgkmcnt(1)
	v_add_f32_e32 v58, v64, v66
	s_waitcnt lgkmcnt(0)
	v_add_f32_e32 v59, v62, v68
	v_mov_b32_e32 v64, v63
	v_mov_b32_e32 v68, v67
	v_pk_mul_f32 v[12:13], v[12:13], v[64:65]
	v_pk_mul_f32 v[14:15], v[14:15], v[68:69]
	v_mov_b32_e32 v76, v75
	v_cvt_pk_bf16_f32 v12, v12, v13
	v_cvt_pk_bf16_f32 v13, v14, v15
	v_cvt_pk_bf16_f32 v14, v8, v9
	v_pk_mul_f32 v[8:9], v[10:11], v[76:77]
	v_and_b32_e32 v10, 0xffff0000, v13
	v_cvt_pk_bf16_f32 v15, v8, v9
	v_lshlrev_b32_e32 v8, 16, v12
	v_and_b32_e32 v9, 0xffff0000, v12
	v_add_f32_e32 v8, v8, v9
	v_lshlrev_b32_e32 v9, 16, v13
	v_add_f32_e32 v9, v9, v10
	v_add_f32_e32 v8, v8, v9
	v_lshlrev_b32_e32 v9, 16, v14
	v_and_b32_e32 v10, 0xffff0000, v14
	v_mul_f32_e32 v5, v5, v65
	v_mul_f32_e32 v1, v1, v73
	v_add_f32_e32 v9, v9, v10
	v_lshlrev_b32_e32 v10, 16, v15
	v_and_b32_e32 v11, 0xffff0000, v15
	v_fmac_f32_e32 v5, v4, v63
	v_mul_f32_e32 v4, v7, v69
	v_fmac_f32_e32 v1, v0, v71
	v_mul_f32_e32 v0, v3, v77
	v_add_f32_e32 v10, v10, v11
	v_fmac_f32_e32 v4, v6, v67
	v_fmac_f32_e32 v0, v2, v75
	v_add_f32_e32 v9, v9, v10
	v_add_f32_e32 v4, v5, v4
	v_add_f32_e32 v0, v1, v0
	v_add_f32_e32 v8, v8, v9
	v_add_f32_e32 v3, v4, v0
	ds_bpermute_b32 v1, v84, v8
	ds_bpermute_b32 v4, v84, v3
	ds_bpermute_b32 v53, v85, v33
	ds_bpermute_b32 v60, v85, v59
	ds_bpermute_b32 v57, v86, v56
	s_waitcnt lgkmcnt(4)
	v_add_f32_e32 v5, v8, v1
	s_waitcnt lgkmcnt(3)
	v_add_f32_e32 v3, v3, v4
	ds_bpermute_b32 v6, v85, v5
	ds_bpermute_b32 v4, v85, v3
	s_waitcnt lgkmcnt(4)
	v_add_f32_e32 v33, v33, v53
	s_waitcnt lgkmcnt(3)
	v_add_f32_e32 v0, v59, v60
	ds_bpermute_b32 v51, v86, v33
	s_waitcnt lgkmcnt(2)
	v_add_f32_e32 v5, v5, v6
	s_waitcnt lgkmcnt(1)
	v_add_f32_e32 v3, v3, v4
	ds_bpermute_b32 v53, v86, v52
	ds_bpermute_b32 v55, v86, v54
	ds_bpermute_b32 v2, v86, v58
	ds_bpermute_b32 v1, v86, v0
	ds_bpermute_b32 v6, v86, v5
	ds_bpermute_b32 v4, v86, v3
	v_add_u32_e32 v8, 24, v32
	v_ashrrev_i32_e32 v9, 31, v8
	v_lshlrev_b64 v[8:9], 13, v[8:9]
	v_lshl_add_u64 v[8:9], v[30:31], 0, v[8:9]
	global_store_dwordx4 v[8:9], v[12:15], off nt
	s_and_saveexec_b64 s[10:11], vcc
	s_cbranch_execz .LBB0_926
	s_waitcnt lgkmcnt(5)
	v_add_f32_e32 v7, v52, v53
	s_waitcnt lgkmcnt(0)
	v_add_f32_e32 v3, v3, v4
	v_add_f32_e32 v4, v33, v51
	v_add_f32_e32 v5, v5, v6
	v_add_f32_e32 v6, v56, v57
	v_cndmask_b32_e64 v7, 0, v7, s[8:9]
	v_add_f32_e32 v0, v0, v1
	v_add_f32_e32 v1, v54, v55
	v_cndmask_b32_e64 v4, 0, v4, s[8:9]
	v_add_f32_e32 v2, v58, v2
	v_cndmask_b32_e64 v6, v7, v6, s[6:7]
	v_cndmask_b32_e64 v1, v4, v1, s[6:7]
	s_ashr_i32 s21, s20, 31
	v_cndmask_b32_e64 v2, v6, v2, s[4:5]
	v_cndmask_b32_e64 v0, v1, v0, s[4:5]
	s_lshl_b64 s[20:21], s[20:21], 2
	v_cndmask_b32_e64 v2, v2, v5, s[2:3]
	v_cndmask_b32_e64 v3, v0, v3, s[2:3]
	v_lshl_add_u64 v[0:1], v[24:25], 0, s[20:21]
	global_atomic_add_f32 v[0:1], v2, off
	v_lshl_add_u64 v[0:1], v[26:27], 0, s[20:21]
	global_atomic_add_f32 v[0:1], v3, off
	s_branch .LBB0_926

; #define LAS __attribute__((address_space(3)))
; #define LDS_WAIT() asm volatile("s_waitcnt lgkmcnt(0)" ::: "memory")
; __device__ __forceinline__ unsigned cvt_pk_bf16(float lo, float hi) { const f32x2 v = {lo, hi}; const bf16x2_t b = __builtin_convertvector(v, bf16x2_t); return __builtin_bit_cast(unsigned, b); }
; __device__ __forceinline__ void p0_item(const float* __restrict__ W, int ldw, int K, bf16_t* __restrict__ WT, int sc, int dn, int k0, const float* __restrict__ gk, LAS float* scr, int lane) {
;     ...
; #pragma unroll 8
;     for (int i = 0; i < 32; ++i) { const int kk = 2 * i + (lane >> 5); float v = __builtin_nontemporal_load(W + (size_t)(k0 + kk) * ldw + sc + (lane & 31)); if (gk) v *= gk[k0 + kk]; scr[kk * 33 + (lane & 31)] = v; }
;     LDS_WAIT(); asm volatile("" ::: "memory");
; #pragma unroll
;     for (int j = 0; j < 4; ++j) { const int n = (lane >> 3) + 8 * j; const LAS float* s = scr + (8 * c) * 33 + n;
;         u32x4 o; o.x = cvt_pk_bf16(s[0 * 33], s[1 * 33]); o.y = cvt_pk_bf16(s[2 * 33], s[3 * 33]); o.z = cvt_pk_bf16(s[4 * 33], s[5 * 33]); o.w = cvt_pk_bf16(s[6 * 33], s[7 * 33]);
;         __builtin_nontemporal_store(o, (u32x4*)(WT + (size_t)(dn + n) * K + k0 + 8 * c)); }
;     LDS_WAIT(); asm volatile("" ::: "memory");
.LBB0_936:
	v_lshl_add_u64 v[32:33], v[20:21], 0, s[6:7]
	v_lshl_add_u64 v[36:37], v[18:19], 0, s[6:7]
	v_lshl_add_u64 v[38:39], v[14:15], 0, s[6:7]
	v_lshl_add_u64 v[40:41], v[12:13], 0, s[6:7]
	v_lshl_add_u64 v[42:43], v[10:11], 0, s[6:7]
	v_lshl_add_u64 v[44:45], v[8:9], 0, s[6:7]
	v_lshl_add_u64 v[46:47], v[6:7], 0, s[6:7]
	v_lshl_add_u64 v[48:49], v[4:5], 0, s[6:7]
	global_load_dword v176, v[32:33], off nt
	global_load_dword v177, v[36:37], off nt
	global_load_dword v178, v[38:39], off nt
	global_load_dword v179, v[40:41], off nt
	global_load_dword v180, v[42:43], off nt
	global_load_dword v181, v[44:45], off nt
	global_load_dword v182, v[46:47], off nt
	global_load_dword v183, v[48:49], off nt
	s_add_u32 s6, s6, 0x40000
	s_addc_u32 s7, s7, 0
	v_lshl_add_u64 v[32:33], v[20:21], 0, s[6:7]
	v_lshl_add_u64 v[36:37], v[18:19], 0, s[6:7]
	v_lshl_add_u64 v[38:39], v[14:15], 0, s[6:7]
	v_lshl_add_u64 v[40:41], v[12:13], 0, s[6:7]
	v_lshl_add_u64 v[42:43], v[10:11], 0, s[6:7]
	v_lshl_add_u64 v[44:45], v[8:9], 0, s[6:7]
	v_lshl_add_u64 v[46:47], v[6:7], 0, s[6:7]
	v_lshl_add_u64 v[48:49], v[4:5], 0, s[6:7]
	global_load_dword v184, v[32:33], off nt
	global_load_dword v185, v[36:37], off nt
	global_load_dword v186, v[38:39], off nt
	global_load_dword v187, v[40:41], off nt
	global_load_dword v188, v[42:43], off nt
	global_load_dword v189, v[44:45], off nt
	global_load_dword v190, v[46:47], off nt
	global_load_dword v191, v[48:49], off nt
	s_add_u32 s6, s6, 0x40000
	s_addc_u32 s7, s7, 0
	v_lshl_add_u64 v[32:33], v[20:21], 0, s[6:7]
	v_lshl_add_u64 v[36:37], v[18:19], 0, s[6:7]
	v_lshl_add_u64 v[38:39], v[14:15], 0, s[6:7]
	v_lshl_add_u64 v[40:41], v[12:13], 0, s[6:7]
	v_lshl_add_u64 v[42:43], v[10:11], 0, s[6:7]
	v_lshl_add_u64 v[44:45], v[8:9], 0, s[6:7]
	v_lshl_add_u64 v[46:47], v[6:7], 0, s[6:7]
	v_lshl_add_u64 v[48:49], v[4:5], 0, s[6:7]
	global_load_dword v192, v[32:33], off nt
	global_load_dword v193, v[36:37], off nt
	global_load_dword v194, v[38:39], off nt
	global_load_dword v195, v[40:41], off nt
	global_load_dword v196, v[42:43], off nt
	global_load_dword v197, v[44:45], off nt
	global_load_dword v198, v[46:47], off nt
	global_load_dword v199, v[48:49], off nt
	s_add_u32 s6, s6, 0x40000
	s_addc_u32 s7, s7, 0
	v_lshl_add_u64 v[32:33], v[20:21], 0, s[6:7]
	v_lshl_add_u64 v[36:37], v[18:19], 0, s[6:7]
	v_lshl_add_u64 v[38:39], v[14:15], 0, s[6:7]
	v_lshl_add_u64 v[40:41], v[12:13], 0, s[6:7]
	v_lshl_add_u64 v[42:43], v[10:11], 0, s[6:7]
	v_lshl_add_u64 v[44:45], v[8:9], 0, s[6:7]
	v_lshl_add_u64 v[46:47], v[6:7], 0, s[6:7]
	v_lshl_add_u64 v[48:49], v[4:5], 0, s[6:7]
	global_load_dword v200, v[32:33], off nt
	global_load_dword v201, v[36:37], off nt
	global_load_dword v202, v[38:39], off nt
	global_load_dword v203, v[40:41], off nt
	global_load_dword v204, v[42:43], off nt
	global_load_dword v205, v[44:45], off nt
	global_load_dword v206, v[46:47], off nt
	global_load_dword v207, v[48:49], off nt
	s_add_u32 s6, s6, 0x40000
	s_addc_u32 s7, s7, 0
	v_add_u32_e32 v40, 0x400, v30
	s_waitcnt vmcnt(30)
	ds_write2_b32 v30, v176, v177 offset1:66
	s_waitcnt vmcnt(28)
	ds_write2_b32 v30, v178, v179 offset0:132 offset1:198
	s_waitcnt vmcnt(26)
	ds_write2_b32 v40, v180, v181 offset0:8 offset1:74
	s_waitcnt vmcnt(24)
	ds_write2_b32 v40, v182, v183 offset0:140 offset1:206
	v_add_u32_e32 v30, 0x840, v30
	v_add_u32_e32 v40, 0x400, v30
	s_waitcnt vmcnt(22)
	ds_write2_b32 v30, v184, v185 offset1:66
	s_waitcnt vmcnt(20)
	ds_write2_b32 v30, v186, v187 offset0:132 offset1:198
	s_waitcnt vmcnt(18)
	ds_write2_b32 v40, v188, v189 offset0:8 offset1:74
	s_waitcnt vmcnt(16)
	ds_write2_b32 v40, v190, v191 offset0:140 offset1:206
	v_add_u32_e32 v30, 0x840, v30
	v_add_u32_e32 v40, 0x400, v30
	s_waitcnt vmcnt(14)
	ds_write2_b32 v30, v192, v193 offset1:66
	s_waitcnt vmcnt(12)
	ds_write2_b32 v30, v194, v195 offset0:132 offset1:198
	s_waitcnt vmcnt(10)
	ds_write2_b32 v40, v196, v197 offset0:8 offset1:74
	s_waitcnt vmcnt(8)
	ds_write2_b32 v40, v198, v199 offset0:140 offset1:206
	v_add_u32_e32 v30, 0x840, v30
	v_add_u32_e32 v40, 0x400, v30
	s_waitcnt vmcnt(6)
	ds_write2_b32 v30, v200, v201 offset1:66
	s_waitcnt vmcnt(4)
	ds_write2_b32 v30, v202, v203 offset0:132 offset1:198
	s_waitcnt vmcnt(2)
	ds_write2_b32 v40, v204, v205 offset0:8 offset1:74
	s_waitcnt vmcnt(0)
	ds_write2_b32 v40, v206, v207 offset0:140 offset1:206
	v_add_u32_e32 v30, 0x840, v30
	s_waitcnt lgkmcnt(0)
	ds_read2_b32 v[8:9], v17 offset0:33 offset1:41
	ds_read2_b32 v[10:11], v17 offset1:8
	ds_read2_b32 v[12:13], v17 offset0:66 offset1:74
	ds_read2_b32 v[14:15], v17 offset0:99 offset1:107
	ds_read2_b32 v[18:19], v17 offset0:132 offset1:140
	ds_read2_b32 v[20:21], v17 offset0:165 offset1:173
	ds_read2_b32 v[30:31], v17 offset0:198 offset1:206
	ds_read2_b32 v[32:33], v17 offset0:231 offset1:239
	v_add_u32_e32 v38, s4, v34
	s_ashr_i32 s3, s2, 31
	v_ashrrev_i32_e32 v39, 31, v38
	v_lshl_add_u64 v[36:37], s[2:3], 1, v[0:1]
	v_lshlrev_b64 v[40:41], 13, v[38:39]
	s_waitcnt lgkmcnt(6)
	v_cvt_pk_bf16_f32 v4, v10, v8
	s_waitcnt lgkmcnt(4)
	v_cvt_pk_bf16_f32 v5, v12, v14
	s_waitcnt lgkmcnt(2)
	v_cvt_pk_bf16_f32 v6, v18, v20
	s_waitcnt lgkmcnt(0)
	v_cvt_pk_bf16_f32 v7, v30, v32
	v_lshl_add_u64 v[40:41], v[36:37], 0, v[40:41]
	v_add_u32_e32 v8, 8, v38
	global_store_dwordx4 v[40:41], v[4:7], off nt
	s_mov_b64 s[6:7], 0
	s_nop 0
	v_cvt_pk_bf16_f32 v4, v11, v9
	v_ashrrev_i32_e32 v9, 31, v8
	v_cvt_pk_bf16_f32 v5, v13, v15
	v_cvt_pk_bf16_f32 v6, v19, v21
	v_cvt_pk_bf16_f32 v7, v31, v33
	v_lshlrev_b64 v[8:9], 13, v[8:9]
	ds_read2_b32 v[10:11], v17 offset0:49 offset1:57
	ds_read2_b32 v[12:13], v17 offset0:16 offset1:24
	ds_read2_b32 v[14:15], v17 offset0:82 offset1:90
	ds_read2_b32 v[18:19], v17 offset0:115 offset1:123
	ds_read2_b32 v[20:21], v17 offset0:148 offset1:156
	ds_read2_b32 v[30:31], v17 offset0:181 offset1:189
	ds_read2_b32 v[32:33], v17 offset0:214 offset1:222
	ds_read2_b32 v[40:41], v17 offset0:247 offset1:255
	v_lshl_add_u64 v[8:9], v[36:37], 0, v[8:9]
	global_store_dwordx4 v[8:9], v[4:7], off nt
	v_add_u32_e32 v8, 16, v38
	v_ashrrev_i32_e32 v9, 31, v8
	v_lshlrev_b64 v[8:9], 13, v[8:9]
	s_waitcnt lgkmcnt(6)
	v_cvt_pk_bf16_f32 v4, v12, v10
	s_waitcnt lgkmcnt(4)
	v_cvt_pk_bf16_f32 v5, v14, v18
	s_waitcnt lgkmcnt(2)
	v_cvt_pk_bf16_f32 v6, v20, v30
	s_waitcnt lgkmcnt(0)
	v_cvt_pk_bf16_f32 v7, v32, v40
	v_lshl_add_u64 v[8:9], v[36:37], 0, v[8:9]
	global_store_dwordx4 v[8:9], v[4:7], off nt
	v_add_u32_e32 v8, 24, v38
	v_ashrrev_i32_e32 v9, 31, v8
	v_lshlrev_b64 v[8:9], 13, v[8:9]
	v_cvt_pk_bf16_f32 v4, v13, v11
	v_cvt_pk_bf16_f32 v5, v15, v19
	v_cvt_pk_bf16_f32 v6, v21, v31
	v_cvt_pk_bf16_f32 v7, v33, v41
	v_lshl_add_u64 v[8:9], v[36:37], 0, v[8:9]
	global_store_dwordx4 v[8:9], v[4:7], off nt
	s_waitcnt lgkmcnt(0)
